# attention without the static s_setprio 1 on waves 4-7 (both halves at priority 0)
# baseline (speedup 1.0000x reference)
; #define AT_GLOADK(k0) do { kreg = *(const u32x4*)(Kb + (size_t)((k0) + (tid >> 3)) * 64 + (tid & 7) * 8); \
;             if (MLA) preg = *(const u32x2*)(Pb + (size_t)((k0) + (tid >> 3)) * 32 + (tid & 7) * 4); } while (0)
; #define AT_GLOADV(k0) do { vreg = *(const u32x4*)(Vb + (size_t)((k0) + (tid >> 3)) * 64 + (tid & 7) * 8); } while (0)
; #define AT_WRITEK(buf) do { *(LAS u32x4*)(lds + (buf) * KBUF + (tid >> 3) * KSTR + (tid & 7) * 16) = kreg; \
;             if (MLA) *(LAS u32x2*)(lds + (buf) * KBUF + (tid >> 3) * KSTR + 128 + (tid & 7) * 8) = preg; } while (0)
; #define AT_WRITEV(buf) do { *(LAS u32x4*)(lds + 2 * KBUF + (buf) * VBUF + (tid >> 3) * VSTR + (tid & 7) * 16) = vreg; } while (0)
; template <bool MLA>
; DI void attn_phase(const int TID, const int BID, LAS unsigned char* lds, const Params& p, bool need_ctx) {
;     ...
;         const int kvh = MLA ? head : (head >> 2);
;         const bf16_t* Kb = P_WSB(OFF_K) + (size_t)(b * NKV + kvh) * NKEY * 64;
;         const bf16_t* Vb = P_WSB(OFF_VT) + (size_t)(b * NKV + kvh) * NKEY * 64;
;         const bf16_t* Pb = P_WSB(OFF_KPE) + (size_t)b * NKEY * 32;
;         bf16x8 qf[NKS];
;         {
;             const bf16_t* qp = P_WSB(OFF_Q) + (size_t)(row0 + wid * 32 + r) * QS + head * DK + hh * 8;
; #pragma unroll
;             for (int ks = 0; ks < NKS; ++ks) qf[ks] = *(const bf16x8*)(qp + ks * 16);
;         }
;         u32x4 kreg, vreg; u32x2 preg = {0u, 0u};
;     ...
;         f32x16 o0, o1, sa0, sa1, sb0, sb1;
; #pragma unroll
;         for (int j = 0; j < 16; ++j) { o0[j] = 0.f; o1[j] = 0.f; }
;         float mrun = -1e30f, lsum = 0.f;
;         if (wid >= 4) __builtin_amdgcn_s_setprio(1);
;         const int ntile = nk >> 6;
;         AT_GLOADK(0); AT_GLOADV(0); AT_WRITEK(0); AT_WRITEV(0);
;         AT_GLOADK(64); AT_WRITEK(1);
;         __syncthreads();
;         AT_QK(sa0, sa1, 0);
;         __syncthreads();
.Lamla_decoded:
	s_mov_b32 s19, s18
	s_lshl_b32 s21, s15, 4
	s_add_i32 s21, s21, s19
	s_mul_i32 s21, s21, 0x48000
	s_add_u32 s2, s26, s21
	s_addc_u32 s3, s27, 0
	v_readlane_b32 s60, v254, 36
	v_readlane_b32 s61, v254, 37
	s_add_u32 s4, s60, s21
	s_addc_u32 s5, s61, 0
	v_readlane_b32 s60, v254, 38
	v_readlane_b32 s61, v254, 39
	s_mul_i32 s21, s15, 0x24000
	s_add_u32 s10, s60, s21
	s_addc_u32 s11, s61, 0
	v_readlane_b32 s60, v254, 27
	v_readlane_b32 s61, v254, 28
	s_mul_i32 s21, s20, 0xc00
	s_mul_i32 s55, s18, 0xc0
	s_add_i32 s21, s21, s55
	s_add_u32 s12, s60, s21
	s_addc_u32 s13, s61, 0
	v_readlane_b32 s60, v254, 34
	v_readlane_b32 s61, v254, 35
	s_lshl_b32 s21, s20, 11
	s_lshl_b32 s55, s18, 7
	s_add_i32 s21, s21, s55
	s_add_u32 s16, s60, s21
	s_addc_u32 s17, s61, 0
	global_load_dwordx4 v[112:115], v171, s[12:13]
	global_load_dwordx4 v[116:119], v171, s[12:13] offset:32
	global_load_dwordx4 v[120:123], v171, s[12:13] offset:64
	global_load_dwordx4 v[124:127], v171, s[12:13] offset:96
	global_load_dwordx4 v[128:131], v171, s[12:13] offset:128
	global_load_dwordx4 v[132:135], v171, s[12:13] offset:160
	global_load_dwordx4 v[136:139], v225, s[2:3]
	global_load_dwordx2 v[208:209], v165, s[10:11]
	s_add_u32 s2, s2, 0x2000
	s_addc_u32 s3, s3, 0
	s_add_u32 s10, s10, 0x1000
	s_addc_u32 s11, s11, 0
	global_load_dwordx4 v[140:143], v225, s[2:3]
	global_load_dwordx2 v[210:211], v165, s[10:11]
	s_add_u32 s2, s2, 0x2000
	s_addc_u32 s3, s3, 0
	s_add_u32 s10, s10, 0x1000
	s_addc_u32 s11, s11, 0
	global_load_dwordx4 v[144:147], v225, s[4:5]
	s_add_u32 s4, s4, 0x2000
	s_addc_u32 s5, s5, 0
	global_load_dwordx4 v[152:155], v225, s[2:3]
	global_load_dwordx2 v[160:161], v165, s[10:11]
	s_add_u32 s2, s2, 0x2000
	s_addc_u32 s3, s3, 0
	s_add_u32 s10, s10, 0x1000
	s_addc_u32 s11, s11, 0
	global_load_dwordx4 v[156:159], v225, s[4:5]
	s_add_u32 s4, s4, 0x2000
	s_addc_u32 s5, s5, 0
	s_mov_b32 s52, 0x3000
	s_mov_b32 s53, 0x6000
	s_mov_b32 s54, 0
	v_mov_b64_e32 v[0:1], 0
	v_mov_b64_e32 v[2:3], 0
	v_mov_b64_e32 v[4:5], 0
	v_mov_b64_e32 v[6:7], 0
	v_mov_b64_e32 v[8:9], 0
	v_mov_b64_e32 v[10:11], 0
	v_mov_b64_e32 v[12:13], 0
	v_mov_b64_e32 v[14:15], 0
	v_mov_b64_e32 v[16:17], 0
	v_mov_b64_e32 v[18:19], 0
	v_mov_b64_e32 v[20:21], 0
	v_mov_b64_e32 v[22:23], 0
	v_mov_b64_e32 v[24:25], 0
	v_mov_b64_e32 v[26:27], 0
	v_mov_b64_e32 v[28:29], 0
	v_mov_b64_e32 v[30:31], 0
	v_mov_b32_e32 v162, 0xf149f2ca
	v_mov_b32_e32 v164, 0xf149f2ca
	v_mov_b32_e32 v163, 0x7149f2ca
	v_mov_b64_e32 v[226:227], 0
	v_mov_b64_e32 v[228:229], 0
	v_mov_b64_e32 v[230:231], 0
	v_mov_b64_e32 v[232:233], 0
	v_mov_b64_e32 v[234:235], 0
	v_mov_b64_e32 v[236:237], 0
	v_mov_b64_e32 v[238:239], 0
	v_mov_b64_e32 v[240:241], 0
	s_barrier
	s_waitcnt vmcnt(7)
	ds_write_b128 v218, v[136:139]
	s_waitcnt vmcnt(6)
	ds_write_b64 v219, v[208:209]
	s_waitcnt vmcnt(5)
	ds_write_b128 v218, v[140:143] offset:13312
	s_waitcnt vmcnt(4)
	ds_write_b64 v219, v[210:211] offset:13312
	s_waitcnt vmcnt(3)
	ds_write_b128 v221, v[144:147]
	s_waitcnt lgkmcnt(0)
	s_barrier
	ds_read_b128 v[136:139], v243 offset:0
	ds_read_b128 v[140:143], v243 offset:6656
	ds_read_b128 v[144:147], v243 offset:32
	ds_read_b128 v[148:151], v243 offset:6688
	s_waitcnt lgkmcnt(3)
	v_mfma_f32_32x32x16_bf16 v[32:47], v[136:139], v[112:115], 0
	ds_read_b128 v[136:139], v243 offset:64
	s_waitcnt lgkmcnt(3)
	v_mfma_f32_32x32x16_bf16 v[48:63], v[140:143], v[112:115], 0
	ds_read_b128 v[140:143], v243 offset:6720
	s_waitcnt lgkmcnt(3)
	v_mfma_f32_32x32x16_bf16 v[32:47], v[144:147], v[116:119], v[32:47]
	ds_read_b128 v[144:147], v243 offset:96
	s_waitcnt lgkmcnt(3)
	v_mfma_f32_32x32x16_bf16 v[48:63], v[148:151], v[116:119], v[48:63]
	ds_read_b128 v[148:151], v243 offset:6752
	s_waitcnt lgkmcnt(3)
	v_mfma_f32_32x32x16_bf16 v[32:47], v[136:139], v[120:123], v[32:47]
	ds_read_b128 v[136:139], v243 offset:128
	s_waitcnt lgkmcnt(3)
	v_mfma_f32_32x32x16_bf16 v[48:63], v[140:143], v[120:123], v[48:63]
	ds_read_b128 v[140:143], v243 offset:6784
	s_waitcnt lgkmcnt(3)
	v_mfma_f32_32x32x16_bf16 v[32:47], v[144:147], v[124:127], v[32:47]
	ds_read_b128 v[144:147], v243 offset:160
	s_waitcnt lgkmcnt(3)
	v_mfma_f32_32x32x16_bf16 v[48:63], v[148:151], v[124:127], v[48:63]
	ds_read_b128 v[148:151], v243 offset:6816
	s_waitcnt lgkmcnt(3)
	v_mfma_f32_32x32x16_bf16 v[32:47], v[136:139], v[128:131], v[32:47]
	s_waitcnt lgkmcnt(2)
	v_mfma_f32_32x32x16_bf16 v[48:63], v[140:143], v[128:131], v[48:63]
	s_waitcnt lgkmcnt(1)
	v_mfma_f32_32x32x16_bf16 v[32:47], v[144:147], v[132:135], v[32:47]
	s_waitcnt lgkmcnt(0)
	v_mfma_f32_32x32x16_bf16 v[48:63], v[148:151], v[132:135], v[48:63]
	s_waitcnt lgkmcnt(0)
	s_nop 7
	s_barrier
	ds_read_b128 v[136:139], v243 offset:13312
	ds_read_b128 v[140:143], v243 offset:19968
	ds_read_b128 v[144:147], v243 offset:13344
	ds_read_b128 v[148:151], v243 offset:20000
	s_waitcnt lgkmcnt(3)
	v_mfma_f32_32x32x16_bf16 v[64:79], v[136:139], v[112:115], 0
	v_max3_f32 v168, v32, v33, v34
	v_max3_f32 v170, v48, v49, v50
	v_max3_f32 v168, v168, v35, v36
	v_max3_f32 v170, v170, v51, v52
	v_max3_f32 v168, v168, v37, v38
	v_max3_f32 v170, v170, v53, v54
	v_max3_f32 v168, v168, v39, v40
	v_max3_f32 v170, v170, v55, v56
	v_max3_f32 v168, v168, v41, v42
	v_max3_f32 v170, v170, v57, v58
	v_max3_f32 v168, v168, v43, v44
	v_max3_f32 v170, v170, v59, v60
	ds_read_b128 v[136:139], v243 offset:13376
	s_mov_b32 s55, s52
	s_mov_b32 s52, s53
	s_mov_b32 s53, s54
	s_mov_b32 s54, s55
	s_mov_b32 s9, 0
	s_waitcnt lgkmcnt(3)
	v_mfma_f32_32x32x16_bf16 v[80:95], v[140:143], v[112:115], 0
	v_max3_f32 v168, v168, v45, v46
	v_max3_f32 v170, v170, v61, v62
	v_max_f32_e32 v168, v168, v47
	v_max_f32_e32 v170, v170, v63
	v_max_f32_e32 v168, v168, v170
	v_mov_b32_e32 v170, v168
	s_nop 1
	v_permlane32_swap_b32_e32 v168, v170
	v_max_f32_e32 v168, v168, v170
	v_mul_f32_e32 v168, 0x3e16c740, v168
	v_cmp_gt_f32_e32 vcc, v168, v164
	s_cbranch_vccz .Lamla_nors_1
	v_max_f32_e32 v170, v162, v168
	v_sub_f32_e32 v166, v162, v170
	v_exp_f32_e32 v166, v166
	v_mov_b32_e32 v162, v170
	v_add_f32_e32 v164, 0x41000000, v170
	v_xor_b32_e32 v163, 0x80000000, v170
	s_mov_b32 s9, 1

; #define AT_GLOADK(k0) do { kreg = *(const u32x4*)(Kb + (size_t)((k0) + (tid >> 3)) * 64 + (tid & 7) * 8); \
;             if (MLA) preg = *(const u32x2*)(Pb + (size_t)((k0) + (tid >> 3)) * 32 + (tid & 7) * 4); } while (0)
; #define AT_GLOADV(k0) do { vreg = *(const u32x4*)(Vb + (size_t)((k0) + (tid >> 3)) * 64 + (tid & 7) * 8); } while (0)
; #define AT_WRITEK(buf) do { *(LAS u32x4*)(lds + (buf) * KBUF + (tid >> 3) * KSTR + (tid & 7) * 16) = kreg; \
;             if (MLA) *(LAS u32x2*)(lds + (buf) * KBUF + (tid >> 3) * KSTR + 128 + (tid & 7) * 8) = preg; } while (0)
; #define AT_WRITEV(buf) do { *(LAS u32x4*)(lds + 2 * KBUF + (buf) * VBUF + (tid >> 3) * VSTR + (tid & 7) * 16) = vreg; } while (0)
; template <bool MLA>
; DI void attn_phase(const int TID, const int BID, LAS unsigned char* lds, const Params& p, bool need_ctx) {
;     ...
;         const int kvh = MLA ? head : (head >> 2);
;         const bf16_t* Kb = P_WSB(OFF_K) + (size_t)(b * NKV + kvh) * NKEY * 64;
;         const bf16_t* Vb = P_WSB(OFF_VT) + (size_t)(b * NKV + kvh) * NKEY * 64;
;         const bf16_t* Pb = P_WSB(OFF_KPE) + (size_t)b * NKEY * 32;
;         bf16x8 qf[NKS];
;         {
;             const bf16_t* qp = P_WSB(OFF_Q) + (size_t)(row0 + wid * 32 + r) * QS + head * DK + hh * 8;
; #pragma unroll
;             for (int ks = 0; ks < NKS; ++ks) qf[ks] = *(const bf16x8*)(qp + ks * 16);
;         }
;         u32x4 kreg, vreg; u32x2 preg = {0u, 0u};
;     ...
;         f32x16 o0, o1, sa0, sa1, sb0, sb1;
; #pragma unroll
;         for (int j = 0; j < 16; ++j) { o0[j] = 0.f; o1[j] = 0.f; }
;         float mrun = -1e30f, lsum = 0.f;
;         if (wid >= 4) __builtin_amdgcn_s_setprio(1);
;         const int ntile = nk >> 6;
;         AT_GLOADK(0); AT_GLOADV(0); AT_WRITEK(0); AT_WRITEV(0);
;         AT_GLOADK(64); AT_WRITEK(1);
;         __syncthreads();
;         AT_QK(sa0, sa1, 0);
;         __syncthreads();
.Lagqa_decoded:
	s_lshr_b32 s19, s18, 2
	s_lshl_b32 s21, s15, 2
	s_add_i32 s21, s21, s19
	s_mul_i32 s21, s21, 0x48000
	s_add_u32 s2, s26, s21
	s_addc_u32 s3, s27, 0
	v_readlane_b32 s60, v254, 36
	v_readlane_b32 s61, v254, 37
	s_add_u32 s4, s60, s21
	s_addc_u32 s5, s61, 0
	v_readlane_b32 s60, v254, 27
	v_readlane_b32 s61, v254, 28
	s_mul_i32 s21, s20, 0x800
	s_mul_i32 s55, s18, 0x80
	s_add_i32 s21, s21, s55
	s_add_u32 s12, s60, s21
	s_addc_u32 s13, s61, 0
	v_readlane_b32 s60, v254, 34
	v_readlane_b32 s61, v254, 35
	s_lshl_b32 s21, s20, 11
	s_lshl_b32 s55, s18, 7
	s_add_i32 s21, s21, s55
	s_add_u32 s16, s60, s21
	s_addc_u32 s17, s61, 0
	global_load_dwordx4 v[112:115], v171, s[12:13]
	global_load_dwordx4 v[116:119], v171, s[12:13] offset:32
	global_load_dwordx4 v[120:123], v171, s[12:13] offset:64
	global_load_dwordx4 v[124:127], v171, s[12:13] offset:96
	global_load_dwordx4 v[136:139], v225, s[2:3]
	s_add_u32 s2, s2, 0x2000
	s_addc_u32 s3, s3, 0
	global_load_dwordx4 v[140:143], v225, s[2:3]
	s_add_u32 s2, s2, 0x2000
	s_addc_u32 s3, s3, 0
	global_load_dwordx4 v[144:147], v225, s[4:5]
	s_add_u32 s4, s4, 0x2000
	s_addc_u32 s5, s5, 0
	global_load_dwordx4 v[152:155], v225, s[2:3]
	s_add_u32 s2, s2, 0x2000
	s_addc_u32 s3, s3, 0
	global_load_dwordx4 v[156:159], v225, s[4:5]
	s_add_u32 s4, s4, 0x2000
	s_addc_u32 s5, s5, 0
	s_mov_b32 s52, 0x3000
	s_mov_b32 s53, 0x6000
	s_mov_b32 s54, 0
	v_mov_b64_e32 v[0:1], 0
	v_mov_b64_e32 v[2:3], 0
	v_mov_b64_e32 v[4:5], 0
	v_mov_b64_e32 v[6:7], 0
	v_mov_b64_e32 v[8:9], 0
	v_mov_b64_e32 v[10:11], 0
	v_mov_b64_e32 v[12:13], 0
	v_mov_b64_e32 v[14:15], 0
	v_mov_b64_e32 v[16:17], 0
	v_mov_b64_e32 v[18:19], 0
	v_mov_b64_e32 v[20:21], 0
	v_mov_b64_e32 v[22:23], 0
	v_mov_b64_e32 v[24:25], 0
	v_mov_b64_e32 v[26:27], 0
	v_mov_b64_e32 v[28:29], 0
	v_mov_b64_e32 v[30:31], 0
	v_mov_b32_e32 v162, 0xf149f2ca
	v_mov_b32_e32 v164, 0xf149f2ca
	v_mov_b32_e32 v163, 0x7149f2ca
	v_mov_b64_e32 v[226:227], 0
	v_mov_b64_e32 v[228:229], 0
	v_mov_b64_e32 v[230:231], 0
	v_mov_b64_e32 v[232:233], 0
	v_mov_b64_e32 v[234:235], 0
	v_mov_b64_e32 v[236:237], 0
	v_mov_b64_e32 v[238:239], 0
	v_mov_b64_e32 v[240:241], 0
	s_barrier
	s_waitcnt vmcnt(4)
	ds_write_b128 v218, v[136:139]
	s_waitcnt vmcnt(3)
	ds_write_b128 v218, v[140:143] offset:9216
	s_waitcnt vmcnt(2)
	ds_write_b128 v221, v[144:147]
	s_waitcnt lgkmcnt(0)
	s_barrier
	ds_read_b128 v[136:139], v243 offset:0
	ds_read_b128 v[140:143], v243 offset:4608
	ds_read_b128 v[144:147], v243 offset:32
	ds_read_b128 v[148:151], v243 offset:4640
	s_waitcnt lgkmcnt(3)
	v_mfma_f32_32x32x16_bf16 v[32:47], v[136:139], v[112:115], 0
	ds_read_b128 v[136:139], v243 offset:64
	s_waitcnt lgkmcnt(3)
	v_mfma_f32_32x32x16_bf16 v[48:63], v[140:143], v[112:115], 0
	ds_read_b128 v[140:143], v243 offset:4672
	s_waitcnt lgkmcnt(3)
	v_mfma_f32_32x32x16_bf16 v[32:47], v[144:147], v[116:119], v[32:47]
	ds_read_b128 v[144:147], v243 offset:96
	s_waitcnt lgkmcnt(3)
	v_mfma_f32_32x32x16_bf16 v[48:63], v[148:151], v[116:119], v[48:63]
	ds_read_b128 v[148:151], v243 offset:4704
	s_waitcnt lgkmcnt(3)
	v_mfma_f32_32x32x16_bf16 v[32:47], v[136:139], v[120:123], v[32:47]
	s_waitcnt lgkmcnt(2)
	v_mfma_f32_32x32x16_bf16 v[48:63], v[140:143], v[120:123], v[48:63]
	s_waitcnt lgkmcnt(1)
	v_mfma_f32_32x32x16_bf16 v[32:47], v[144:147], v[124:127], v[32:47]
	s_waitcnt lgkmcnt(0)
	v_mfma_f32_32x32x16_bf16 v[48:63], v[148:151], v[124:127], v[48:63]
	s_waitcnt lgkmcnt(0)
	s_nop 7
	s_barrier
	ds_read_b128 v[136:139], v243 offset:9216
	ds_read_b128 v[140:143], v243 offset:13824
	ds_read_b128 v[144:147], v243 offset:9248
	ds_read_b128 v[148:151], v243 offset:13856
	s_waitcnt lgkmcnt(3)
	v_mfma_f32_32x32x16_bf16 v[64:79], v[136:139], v[112:115], 0
	v_max3_f32 v168, v32, v33, v34
	v_max3_f32 v170, v48, v49, v50
	v_max3_f32 v168, v168, v35, v36
	v_max3_f32 v170, v170, v51, v52
	v_max3_f32 v168, v168, v37, v38
	v_max3_f32 v170, v170, v53, v54
	v_max3_f32 v168, v168, v39, v40
	v_max3_f32 v170, v170, v55, v56
	v_max3_f32 v168, v168, v41, v42
	v_max3_f32 v170, v170, v57, v58
	v_max3_f32 v168, v168, v43, v44
	v_max3_f32 v170, v170, v59, v60
	v_max3_f32 v168, v168, v45, v46
	v_max3_f32 v170, v170, v61, v62
	v_max_f32_e32 v168, v168, v47
	v_max_f32_e32 v170, v170, v63
	v_max_f32_e32 v168, v168, v170
	ds_read_b128 v[136:139], v243 offset:9280
	s_mov_b32 s55, s52
	s_mov_b32 s52, s53
	s_mov_b32 s53, s54
	s_mov_b32 s54, s55
	s_mov_b32 s9, 0
	s_waitcnt lgkmcnt(3)
	v_mfma_f32_32x32x16_bf16 v[80:95], v[140:143], v[112:115], 0
	v_mov_b32_e32 v170, v168
	s_nop 1
	v_permlane32_swap_b32_e32 v168, v170
	v_max_f32_e32 v168, v168, v170
	v_mul_f32_e32 v168, 0x3e38aa3b, v168
	v_cmp_gt_f32_e32 vcc, v168, v164
	s_cbranch_vccz .Lagqa_nors_1
	v_max_f32_e32 v170, v162, v168
	v_sub_f32_e32 v166, v162, v170
	v_exp_f32_e32 v166, v166
	v_mov_b32_e32 v162, v170
	v_add_f32_e32 v164, 0x41000000, v170
	v_xor_b32_e32 v163, 0x80000000, v170
	s_mov_b32 s9, 1
